# v20: fp4 table build moved from phase 0 into the idle tail of non-RWKV blocks in phase 3
# speedup vs baseline: 1.0451x; 1.0213x over previous
.LBB0_17:
	s_or_b64 exec, exec, s[4:5]
	s_load_dword s33, s[0:1], 0x290
	v_lshl_add_u32 v104, s2, 8, v100
	v_and_b32_e32 v96, 63, v100
	v_and_b32_e32 v101, 31, v100
	v_ashrrev_i32_e32 v70, 6, v104
	s_movk_i32 s0, 0x4000
	s_waitcnt lgkmcnt(0)
	s_lshl_b32 s24, s33, 2
	v_cmp_gt_i32_e32 vcc, s0, v70
	v_lshrrev_b32_e32 v107, 5, v96
	v_lshlrev_b32_e32 v102, 2, v101
	v_mbcnt_lo_u32_b32 v139, -1, 0
	v_lshlrev_b32_e32 v98, 4, v101
	s_mov_b64 s[16:17], exec
	s_branch .LBB0_22

.LBB0_583:
	s_or_b64 exec, exec, s[60:61]
	s_waitcnt vmcnt(0)
	s_cmp_lt_u32 s2, 0x100
	s_cbranch_scc1 .Lmy_tq_skip
	v_ashrrev_i32_e32 v70, 6, v104
	v_subrev_u32_e32 v70, 0x400, v70
	s_movk_i32 s24, 0x400
	v_mbcnt_lo_u32_b32 v255, -1, 0
	v_mov_b32_e32 v242, v98
	v_mov_b32_e32 v244, v102
	s_mov_b64 s[22:23], exec
	v_mbcnt_hi_u32_b32 v0, -1, v255
	v_and_b32_e32 v1, 64, v0
	v_add_u32_e32 v1, 64, v1
	v_xor_b32_e32 v2, 16, v0
	v_cmp_lt_i32_e32 vcc, v2, v1
	v_readlane_b32 s36, v238, 0
	v_readlane_b32 s37, v238, 1
	v_cndmask_b32_e32 v2, v0, v2, vcc
	v_lshlrev_b32_e32 v71, 2, v2
	v_xor_b32_e32 v2, 8, v0
	v_cmp_lt_i32_e32 vcc, v2, v1
	v_readlane_b32 s38, v238, 2
	v_readlane_b32 s39, v238, 3
	v_cndmask_b32_e32 v2, v0, v2, vcc
	v_lshlrev_b32_e32 v72, 2, v2
	v_xor_b32_e32 v2, 4, v0
	v_cmp_lt_i32_e32 vcc, v2, v1
	v_readlane_b32 s40, v238, 4
	v_readlane_b32 s41, v238, 5
	v_cndmask_b32_e32 v2, v0, v2, vcc
	v_lshlrev_b32_e32 v73, 2, v2
	v_xor_b32_e32 v2, 2, v0
	v_cmp_lt_i32_e32 vcc, v2, v1
	v_readlane_b32 s42, v238, 6
	v_readlane_b32 s43, v238, 7
	v_cndmask_b32_e32 v2, v0, v2, vcc
	v_lshlrev_b32_e32 v74, 2, v2
	v_xor_b32_e32 v2, 1, v0
	v_readlane_b32 s44, v238, 8
	v_readlane_b32 s45, v238, 9
	v_readlane_b32 s46, v238, 10
	v_readlane_b32 s47, v238, 11
	v_readlane_b32 s48, v238, 12
	v_readlane_b32 s49, v238, 13
	v_readlane_b32 s50, v238, 14
	v_readlane_b32 s51, v238, 15
	v_cmp_lt_i32_e32 vcc, v2, v1
	v_mov_b32_e32 v77, s49
	v_mov_b32_e32 v78, s51
	v_mov_b32_e32 v79, s48
	v_mov_b32_e32 v80, s50
	v_readlane_b32 s36, v238, 16
	v_mov_b32_e32 v247, 0
	v_cndmask_b32_e32 v0, v0, v2, vcc
	v_readlane_b32 s40, v238, 20
	v_readlane_b32 s41, v238, 21
	v_readlane_b32 s42, v238, 22
	v_readlane_b32 s43, v238, 23
	v_mov_b32_e32 v243, v247
	v_cmp_eq_u32_e64 s[0:1], 0, v101
	v_lshlrev_b32_e32 v75, 2, v0
	v_lshl_or_b32 v76, v70, 1, v107
	s_movk_i32 s12, 0x800
	s_mov_b64 s[10:11], 0
	s_movk_i32 s13, 0x3fff
	v_lshlrev_b32_e32 v34, 2, v244
	v_mov_b32_e32 v35, v247
	v_mov_b32_e32 v81, s41
	v_mov_b32_e32 v82, s43
	v_mov_b32_e32 v83, s40
	v_mov_b32_e32 v84, s42
	s_mov_b32 s94, 0x40c00000
	s_mov_b32 s95, 0x3e800000
	s_mov_b32 s96, 0x3f400000
	s_mov_b32 s97, 0x3fa00000
	s_mov_b32 s14, 0x3fe00000
	s_mov_b32 s15, 0x40600000
	s_mov_b32 s3, 0x40200000
	s_mov_b32 s20, 0x40a00000
	v_readlane_b32 s37, v238, 17
	v_readlane_b32 s38, v238, 18
	v_readlane_b32 s39, v238, 19
	v_readlane_b32 s44, v238, 24
	v_readlane_b32 s45, v238, 25
	v_readlane_b32 s46, v238, 26
	v_readlane_b32 s47, v238, 27
	v_readlane_b32 s48, v238, 28
	v_readlane_b32 s49, v238, 29
	v_readlane_b32 s50, v238, 30
	v_readlane_b32 s51, v238, 31
	s_branch .Lmy_tq_20
.Lmy_tq_19:
	s_or_b64 exec, exec, s[18:19]
	v_add_u32_e32 v70, s24, v70
	v_cmp_lt_i32_e32 vcc, s13, v70
	s_or_b64 s[10:11], vcc, s[10:11]
	v_add_u32_e32 v76, s12, v76
	s_andn2_b64 exec, exec, s[10:11]
	s_cbranch_execz .Lmy_tq_done
.Lmy_tq_20:
	v_and_b32_e32 v85, 0x3fff, v76
	v_cmp_lt_i32_e64 s[16:17], s13, v76
	v_lshlrev_b32_e32 v246, 12, v85
	s_nop 0
	v_cndmask_b32_e64 v1, v77, v78, s[16:17]
	v_cndmask_b32_e64 v0, v79, v80, s[16:17]
	v_lshl_add_u64 v[0:1], v[0:1], 0, v[246:247]
	v_lshl_add_u64 v[12:13], v[0:1], 0, v[34:35]
	global_load_dwordx4 v[16:19], v[12:13], off
	global_load_dwordx4 v[0:3], v[12:13], off offset:512
	global_load_dwordx4 v[20:23], v[12:13], off offset:1024
	global_load_dwordx4 v[4:7], v[12:13], off offset:1536
	global_load_dwordx4 v[24:27], v[12:13], off offset:2048
	global_load_dwordx4 v[8:11], v[12:13], off offset:2560
	global_load_dwordx4 v[28:31], v[12:13], off offset:3072
	s_nop 0
	global_load_dwordx4 v[12:15], v[12:13], off offset:3584
	v_cndmask_b32_e64 v37, v81, v82, s[16:17]
	v_cndmask_b32_e64 v36, v83, v84, s[16:17]
	v_lshlrev_b32_e32 v246, 9, v85
	v_lshl_add_u64 v[36:37], v[36:37], 0, v[246:247]
	v_lshl_add_u64 v[36:37], v[36:37], 0, v[242:243]
	s_waitcnt vmcnt(7)
	v_max3_f32 v60, |v16|, 0, |v17|
	v_max3_f32 v60, v60, |v18|, |v19|
	s_waitcnt vmcnt(6)
	v_max3_f32 v60, v60, |v0|, |v1|
	v_max3_f32 v60, v60, |v2|, |v3|
	s_waitcnt vmcnt(5)
	v_max3_f32 v60, v60, |v20|, |v21|
	v_max3_f32 v60, v60, |v22|, |v23|
	s_waitcnt vmcnt(4)
	v_max3_f32 v60, v60, |v4|, |v5|
	v_max3_f32 v60, v60, |v6|, |v7|
	s_waitcnt vmcnt(3)
	v_max3_f32 v60, v60, |v24|, |v25|
	v_max3_f32 v60, v60, |v26|, |v27|
	s_waitcnt vmcnt(2)
	v_max3_f32 v60, v60, |v8|, |v9|
	v_max3_f32 v60, v60, |v10|, |v11|
	s_waitcnt vmcnt(1)
	v_max3_f32 v60, v60, |v28|, |v29|
	v_max3_f32 v60, v60, |v30|, |v31|
	s_waitcnt vmcnt(0)
	v_max3_f32 v60, v60, |v12|, |v13|
	v_max3_f32 v60, v60, |v14|, |v15|
	ds_bpermute_b32 v61, v71, v60
	v_cmp_ngt_f32_e32 vcc, 0, v28
	v_and_b32_e32 v86, 0x7fffffff, v24
	v_and_b32_e32 v66, 0x7fffffff, v25
	v_cndmask_b32_e64 v246, 8, 0, vcc
	s_waitcnt lgkmcnt(0)
	v_max_f32_e32 v61, v61, v61
	v_max_f32_e32 v60, v60, v61
	ds_bpermute_b32 v61, v72, v60
	v_cmp_ngt_f32_e32 vcc, 0, v24
	v_and_b32_e32 v50, 0x7fffffff, v18
	v_and_b32_e32 v51, 0x7fffffff, v22
	v_cndmask_b32_e64 v88, 8, 0, vcc
	s_waitcnt lgkmcnt(0)
	v_max_f32_e32 v61, v61, v61
	v_max_f32_e32 v60, v60, v61
	ds_bpermute_b32 v61, v73, v60
	v_cmp_ngt_f32_e32 vcc, 0, v20
	v_and_b32_e32 v87, 0x7fffffff, v28
	v_and_b32_e32 v46, 0x7fffffff, v19
	v_cndmask_b32_e64 v89, 8, 0, vcc
	s_waitcnt lgkmcnt(0)
	v_max_f32_e32 v61, v61, v61
	v_max_f32_e32 v64, v60, v61
	ds_bpermute_b32 v65, v74, v64
	v_cmp_ngt_f32_e32 vcc, 0, v16
	v_and_b32_e32 v60, 0x7fffffff, v17
	v_and_b32_e32 v61, 0x7fffffff, v21
	v_cndmask_b32_e64 v90, 8, 0, vcc
	v_cmp_ngt_f32_e32 vcc, 0, v29
	v_and_b32_e32 v47, 0x7fffffff, v23
	v_and_b32_e32 v67, 0x7fffffff, v29
	v_cndmask_b32_e64 v91, 8, 0, vcc
	v_cmp_ngt_f32_e32 vcc, 0, v25
	v_and_b32_e32 v42, 0x7fffffff, v0
	v_and_b32_e32 v43, 0x7fffffff, v4
	v_cndmask_b32_e64 v92, 8, 0, vcc
	v_cmp_ngt_f32_e32 vcc, 0, v21
	v_and_b32_e32 v44, 0x7fffffff, v8
	v_and_b32_e32 v45, 0x7fffffff, v12
	v_cndmask_b32_e64 v93, 8, 0, vcc
	v_cmp_ngt_f32_e32 vcc, 0, v17
	s_waitcnt lgkmcnt(0)
	v_max_f32_e32 v17, v65, v65
	v_max_f32_e32 v17, v64, v17
	ds_bpermute_b32 v21, v75, v17
	v_and_b32_e32 v64, 0x7fffffff, v16
	v_and_b32_e32 v65, 0x7fffffff, v20
	v_cndmask_b32_e64 v94, 8, 0, vcc
	v_and_b32_e32 v52, 0x7fffffff, v2
	s_waitcnt lgkmcnt(0)
	v_max_f32_e32 v16, v21, v21
	v_max_f32_e32 v17, v17, v16
	v_div_scale_f32 v16, s[18:19], v17, v17, s94
	v_rcp_f32_e32 v20, v16
	v_div_scale_f32 v21, vcc, s94, v17, s94
	v_and_b32_e32 v53, 0x7fffffff, v6
	v_fma_f32 v24, -v16, v20, 1.0
	v_fmac_f32_e32 v20, v24, v20
	v_mul_f32_e32 v24, v21, v20
	v_fma_f32 v25, -v16, v24, v21
	v_fmac_f32_e32 v24, v25, v20
	v_fma_f32 v16, -v16, v24, v21
	v_div_fmas_f32 v16, v16, v20, v24
	v_div_fixup_f32 v16, v16, v17, s94
	v_cmp_lt_f32_e32 vcc, 0, v17
	v_and_b32_e32 v58, 0x7fffffff, v9
	v_and_b32_e32 v59, 0x7fffffff, v13
	v_cndmask_b32_e32 v16, 1.0, v16, vcc
	v_pk_mul_f32 v[68:69], v[64:65], v[16:17] op_sel_hi:[1,0]
	v_pk_mul_f32 v[64:65], v[60:61], v[16:17] op_sel_hi:[1,0]
	v_cmp_le_f32_e64 s[18:19], s95, v68
	v_pk_mul_f32 v[60:61], v[50:51], v[16:17] op_sel_hi:[1,0]
	v_pk_mul_f32 v[50:51], v[46:47], v[16:17] op_sel_hi:[1,0]
	v_cndmask_b32_e64 v20, 0, 1, s[18:19]
	v_cmp_le_f32_e64 s[18:19], s96, v68
	v_and_b32_e32 v54, 0x7fffffff, v1
	v_and_b32_e32 v55, 0x7fffffff, v5
	v_cndmask_b32_e64 v21, 0, 1, s[18:19]
	v_cmp_le_f32_e64 s[18:19], s14, v68
	v_and_b32_e32 v56, 0x7fffffff, v10
	v_and_b32_e32 v57, 0x7fffffff, v14
	v_cndmask_b32_e64 v95, 0, 1, s[18:19]
	v_cmp_le_f32_e64 s[18:19], s95, v64
	v_and_b32_e32 v62, 0x7fffffff, v26
	v_and_b32_e32 v63, 0x7fffffff, v30
	v_cndmask_b32_e64 v24, 0, 1, s[18:19]
	v_cmp_le_f32_e64 s[18:19], s96, v64
	v_and_b32_e32 v48, 0x7fffffff, v27
	v_and_b32_e32 v49, 0x7fffffff, v31
	v_cndmask_b32_e64 v25, 0, 1, s[18:19]
	v_cmp_le_f32_e64 s[18:19], s14, v64
	v_pk_mul_f32 v[48:49], v[48:49], v[16:17] op_sel_hi:[1,0]
	v_and_b32_e32 v40, 0x7fffffff, v11
	v_cndmask_b32_e64 v28, 0, 1, s[18:19]
	v_cmp_le_f32_e64 s[18:19], s95, v60
	v_and_b32_e32 v41, 0x7fffffff, v15
	v_and_b32_e32 v38, 0x7fffffff, v3
	v_cndmask_b32_e64 v29, 0, 1, s[18:19]
	v_cmp_le_f32_e64 s[18:19], s96, v60
	v_and_b32_e32 v39, 0x7fffffff, v7
	s_nop 0
	v_cndmask_b32_e64 v46, 0, 1, s[18:19]
	v_cmp_le_f32_e64 s[18:19], s14, v60
	s_nop 1
	v_cndmask_b32_e64 v248, 0, 1, s[18:19]
	v_cmp_le_f32_e64 s[18:19], s95, v50
	s_nop 1
	v_cndmask_b32_e64 v47, 0, 1, s[18:19]
	v_cmp_le_f32_e64 s[18:19], s97, v68
	s_nop 1
	v_addc_co_u32_e64 v245, s[18:19], v20, v21, s[18:19]
	v_cmp_le_f32_e64 s[18:19], s97, v64
	s_nop 1
	v_addc_co_u32_e64 v20, s[18:19], v24, v25, s[18:19]
	v_cmp_le_f32_e64 s[18:19], s97, v60
	v_pk_mul_f32 v[24:25], v[52:53], v[16:17] op_sel_hi:[1,0]
	s_nop 0
	v_addc_co_u32_e64 v249, s[18:19], v29, v46, s[18:19]
	v_cmp_le_f32_e64 s[18:19], s3, v64
	s_nop 1
	v_addc_co_u32_e64 v250, s[18:19], v20, v28, s[18:19]
	v_cmp_le_f32_e64 s[18:19], s96, v50
	v_pk_mul_f32 v[28:29], v[54:55], v[16:17] op_sel_hi:[1,0]
	s_nop 0
	v_cndmask_b32_e64 v20, 0, 1, s[18:19]
	v_cmp_le_f32_e64 s[18:19], s97, v50
	s_nop 1
	v_addc_co_u32_e64 v251, s[18:19], v47, v20, s[18:19]
	v_pk_mul_f32 v[46:47], v[44:45], v[16:17] op_sel_hi:[1,0]
	v_pk_mul_f32 v[44:45], v[42:43], v[16:17] op_sel_hi:[1,0]
	v_pk_mul_f32 v[42:43], v[58:59], v[16:17] op_sel_hi:[1,0]
	v_cmp_le_f32_e64 s[18:19], s95, v44
	v_pk_mul_f32 v[20:21], v[56:57], v[16:17] op_sel_hi:[1,0]
	s_nop 0
	v_cndmask_b32_e64 v109, 0, 1, s[18:19]
	v_cmp_le_f32_e64 s[18:19], s96, v44
	s_nop 1
	v_cndmask_b32_e64 v252, 0, 1, s[18:19]
	v_cmp_le_f32_e64 s[18:19], s95, v69
	s_nop 1
	v_cndmask_b32_e64 v52, 0, 1, s[18:19]
	v_cmp_le_f32_e64 s[18:19], s96, v69
	s_nop 1
	v_cndmask_b32_e64 v53, 0, 1, s[18:19]
	v_cmp_le_f32_e64 s[18:19], s97, v69
	s_nop 1
	v_addc_co_u32_e64 v58, s[18:19], v52, v53, s[18:19]
	v_cmp_le_f32_e64 s[18:19], s14, v69
	s_nop 1
	v_cndmask_b32_e64 v59, 0, 1, s[18:19]
	v_cmp_le_f32_e64 s[18:19], s95, v65
	s_nop 1
	v_cndmask_b32_e64 v52, 0, 1, s[18:19]
	v_cmp_le_f32_e64 s[18:19], s96, v65
	s_nop 1
	v_cndmask_b32_e64 v53, 0, 1, s[18:19]
	v_cmp_le_f32_e64 s[18:19], s97, v65
	s_nop 1
	v_addc_co_u32_e64 v52, s[18:19], v52, v53, s[18:19]
	v_cmp_le_f32_e64 s[18:19], s14, v65
	s_nop 1
	v_cndmask_b32_e64 v53, 0, 1, s[18:19]
	v_cmp_le_f32_e64 s[18:19], s3, v65
	s_nop 1
	v_addc_co_u32_e64 v253, s[18:19], v52, v53, s[18:19]
	v_cmp_le_f32_e64 s[18:19], s95, v61
	s_nop 1
	v_cndmask_b32_e64 v52, 0, 1, s[18:19]
	v_cmp_le_f32_e64 s[18:19], s96, v61
	s_nop 1
	v_cndmask_b32_e64 v53, 0, 1, s[18:19]
	v_cmp_le_f32_e64 s[18:19], s97, v61
	s_nop 1
	v_addc_co_u32_e64 v112, s[18:19], v52, v53, s[18:19]
	v_cmp_le_f32_e64 s[18:19], s14, v61
	s_nop 1
	v_cndmask_b32_e64 v113, 0, 1, s[18:19]
	v_cmp_le_f32_e64 s[18:19], s95, v51
	s_nop 1
	v_cndmask_b32_e64 v52, 0, 1, s[18:19]
	v_cmp_le_f32_e64 s[18:19], s96, v51
	s_nop 1
	v_cndmask_b32_e64 v53, 0, 1, s[18:19]
	v_cmp_le_f32_e64 s[18:19], s97, v51
	s_nop 1
	v_addc_co_u32_e64 v114, s[18:19], v52, v53, s[18:19]
	v_cmp_le_f32_e64 s[18:19], s95, v45
	v_pk_mul_f32 v[52:53], v[86:87], v[16:17] op_sel_hi:[1,0]
	s_nop 0
	v_cndmask_b32_e64 v115, 0, 1, s[18:19]
	v_cmp_le_f32_e64 s[18:19], s96, v45
	s_nop 1
	v_cndmask_b32_e64 v116, 0, 1, s[18:19]
	v_cmp_le_f32_e64 s[18:19], s95, v52
	s_nop 1
	v_cndmask_b32_e64 v54, 0, 1, s[18:19]
	v_cmp_le_f32_e64 s[18:19], s96, v52
	s_nop 1
	v_cndmask_b32_e64 v55, 0, 1, s[18:19]
	v_cmp_le_f32_e64 s[18:19], s97, v52
	s_nop 1
	v_addc_co_u32_e64 v86, s[18:19], v54, v55, s[18:19]
	v_cmp_le_f32_e64 s[18:19], s14, v52
	v_pk_mul_f32 v[54:55], v[66:67], v[16:17] op_sel_hi:[1,0]
	s_nop 0
	v_cndmask_b32_e64 v87, 0, 1, s[18:19]
	v_cmp_le_f32_e64 s[18:19], s95, v54
	s_nop 1
	v_cndmask_b32_e64 v56, 0, 1, s[18:19]
	v_cmp_le_f32_e64 s[18:19], s96, v54
	s_nop 1
	v_cndmask_b32_e64 v57, 0, 1, s[18:19]
	v_cmp_le_f32_e64 s[18:19], s97, v54
	s_nop 1
	v_addc_co_u32_e64 v56, s[18:19], v56, v57, s[18:19]
	v_cmp_le_f32_e64 s[18:19], s14, v54
	s_nop 1
	v_cndmask_b32_e64 v57, 0, 1, s[18:19]
	v_cmp_le_f32_e64 s[18:19], s3, v54
	s_nop 1
	v_addc_co_u32_e64 v66, s[18:19], v56, v57, s[18:19]
	v_pk_mul_f32 v[56:57], v[62:63], v[16:17] op_sel_hi:[1,0]
	s_nop 0
	v_cmp_le_f32_e64 s[18:19], s95, v56
	s_nop 1
	v_cndmask_b32_e64 v62, 0, 1, s[18:19]
	v_cmp_le_f32_e64 s[18:19], s96, v56
	s_nop 1
	v_cndmask_b32_e64 v63, 0, 1, s[18:19]
	v_cmp_le_f32_e64 s[18:19], s97, v56
	s_nop 1
	v_addc_co_u32_e64 v62, s[18:19], v62, v63, s[18:19]
	v_cmp_le_f32_e64 s[18:19], s14, v56
	s_nop 1
	v_cndmask_b32_e64 v63, 0, 1, s[18:19]
	v_cmp_le_f32_e64 s[18:19], s95, v48
	s_nop 1
	v_cndmask_b32_e64 v67, 0, 1, s[18:19]
	v_cmp_le_f32_e64 s[18:19], s96, v48
	s_nop 1
	v_cndmask_b32_e64 v254, 0, 1, s[18:19]
	v_cmp_le_f32_e64 s[18:19], s97, v48
	s_nop 1
	v_addc_co_u32_e64 v67, s[18:19], v67, v254, s[18:19]
	v_cmp_le_f32_e64 s[18:19], s95, v46
	s_nop 1
	v_cndmask_b32_e64 v254, 0, 1, s[18:19]
	v_cmp_le_f32_e64 s[18:19], s96, v46
	s_nop 1
	v_cndmask_b32_e64 v118, 0, 1, s[18:19]
	v_cmp_le_f32_e64 s[18:19], s95, v53
	s_nop 1
	v_cndmask_b32_e64 v119, 0, 1, s[18:19]
	v_cmp_le_f32_e64 s[18:19], s96, v53
	s_nop 1
	v_cndmask_b32_e64 v120, 0, 1, s[18:19]
	v_cmp_le_f32_e64 s[18:19], s97, v53
	s_nop 1
	v_addc_co_u32_e64 v119, s[18:19], v119, v120, s[18:19]
	v_cmp_le_f32_e64 s[18:19], s14, v53
	s_nop 1
	v_cndmask_b32_e64 v120, 0, 1, s[18:19]
	v_cmp_le_f32_e64 s[18:19], s3, v68
	s_nop 1
	v_addc_co_u32_e64 v95, s[18:19], v245, v95, s[18:19]
	v_cmp_le_f32_e64 s[18:19], s3, v69
	s_nop 1
	v_addc_co_u32_e64 v58, s[18:19], v58, v59, s[18:19]
	v_cmp_le_f32_e64 s[18:19], s3, v52
	s_nop 1
	v_addc_co_u32_e64 v59, s[18:19], v86, v87, s[18:19]
	v_cmp_le_f32_e64 s[18:19], s3, v53
	s_nop 1
	v_addc_co_u32_e64 v86, s[18:19], v119, v120, s[18:19]
	v_cmp_le_f32_e64 s[18:19], s15, v68
	s_nop 1
	v_cndmask_b32_e64 v87, 0, 1, s[18:19]
	v_cmp_le_f32_e64 s[18:19], s15, v69
	s_nop 1
	v_cndmask_b32_e64 v245, 0, 1, s[18:19]
	v_cmp_le_f32_e64 s[18:19], s15, v52
	s_nop 1
	v_cndmask_b32_e64 v119, 0, 1, s[18:19]
	v_cmp_le_f32_e64 s[18:19], s15, v53
	s_nop 1
	v_cndmask_b32_e64 v120, 0, 1, s[18:19]
	v_cmp_le_f32_e64 s[18:19], s20, v53
	s_nop 1
	v_addc_co_u32_e64 v53, s[18:19], v86, v120, s[18:19]
	v_cmp_le_f32_e64 s[18:19], s20, v52
	s_nop 1
	v_addc_co_u32_e64 v52, s[18:19], v59, v119, s[18:19]
	v_cmp_le_f32_e64 s[18:19], s20, v69
	s_nop 1
	v_addc_co_u32_e64 v58, s[18:19], v58, v245, s[18:19]
	v_cmp_le_f32_e64 s[18:19], s20, v68
	s_nop 1
	v_addc_co_u32_e64 v59, s[18:19], v95, v87, s[18:19]
	v_cmp_le_f32_e64 s[18:19], s95, v55
	s_nop 1
	v_cndmask_b32_e64 v68, 0, 1, s[18:19]
	v_cmp_le_f32_e64 s[18:19], s96, v55
	s_nop 1
	v_cndmask_b32_e64 v69, 0, 1, s[18:19]
	v_cmp_le_f32_e64 s[18:19], s97, v55
	s_nop 1
	v_addc_co_u32_e64 v68, s[18:19], v68, v69, s[18:19]
	v_cmp_le_f32_e64 s[18:19], s14, v55
	s_nop 1
	v_cndmask_b32_e64 v69, 0, 1, s[18:19]
	v_cmp_le_f32_e64 s[18:19], s3, v55
	s_nop 1
	v_addc_co_u32_e64 v68, s[18:19], v68, v69, s[18:19]
	v_cmp_le_f32_e64 s[18:19], s15, v64
	s_nop 1
	v_cndmask_b32_e64 v69, 0, 1, s[18:19]
	v_cmp_le_f32_e64 s[18:19], s15, v65
	s_nop 1
	v_cndmask_b32_e64 v86, 0, 1, s[18:19]
	v_cmp_le_f32_e64 s[18:19], s15, v54
	s_nop 1
	v_cndmask_b32_e64 v87, 0, 1, s[18:19]
	v_cmp_le_f32_e64 s[18:19], s15, v55
	s_nop 1
	v_cndmask_b32_e64 v95, 0, 1, s[18:19]
	v_cmp_le_f32_e64 s[18:19], s20, v55
	s_nop 1
	v_addc_co_u32_e64 v55, s[18:19], v68, v95, s[18:19]
	v_cmp_le_f32_e64 s[18:19], s20, v54
	v_or_b32_e32 v55, v55, v91
	v_lshlrev_b32_e32 v55, 4, v55
	v_addc_co_u32_e64 v54, s[18:19], v66, v87, s[18:19]
	v_cmp_le_f32_e64 s[18:19], s20, v65
	v_or_b32_e32 v54, v54, v92
	v_lshlrev_b32_e32 v54, 4, v54
	v_addc_co_u32_e64 v65, s[18:19], v253, v86, s[18:19]
	v_cmp_le_f32_e64 s[18:19], s20, v64
	v_or3_b32 v246, v53, v246, v55
	v_or3_b32 v52, v52, v88, v54
	v_addc_co_u32_e64 v64, s[18:19], v250, v69, s[18:19]
	v_cmp_le_f32_e64 s[18:19], s95, v57
	v_or_b32_e32 v64, v64, v94
	v_or_b32_e32 v65, v65, v93
	v_cndmask_b32_e64 v53, 0, 1, s[18:19]
	v_cmp_le_f32_e64 s[18:19], s96, v57
	v_lshlrev_b32_e32 v64, 4, v64
	v_lshlrev_b32_e32 v65, 4, v65
	v_cndmask_b32_e64 v54, 0, 1, s[18:19]
	v_cmp_le_f32_e64 s[18:19], s97, v57
	v_or3_b32 v59, v59, v90, v64
	v_or3_b32 v58, v58, v89, v65
	v_addc_co_u32_e64 v53, s[18:19], v53, v54, s[18:19]
	v_cmp_le_f32_e64 s[18:19], s14, v57
	s_nop 1
	v_cndmask_b32_e64 v54, 0, 1, s[18:19]
	v_cmp_le_f32_e64 s[18:19], s3, v57
	s_nop 1
	v_addc_co_u32_e64 v53, s[18:19], v53, v54, s[18:19]
	v_cmp_le_f32_e64 s[18:19], s3, v56
	s_nop 1
	v_addc_co_u32_e64 v54, s[18:19], v62, v63, s[18:19]
	v_cmp_le_f32_e64 s[18:19], s3, v61
	s_nop 1
	v_addc_co_u32_e64 v55, s[18:19], v112, v113, s[18:19]
	v_cmp_le_f32_e64 s[18:19], s3, v60
	s_nop 1
	v_addc_co_u32_e64 v62, s[18:19], v249, v248, s[18:19]
	v_cmp_le_f32_e64 s[18:19], s15, v57
	s_nop 1
	v_cndmask_b32_e64 v63, 0, 1, s[18:19]
	v_cmp_le_f32_e64 s[18:19], s15, v56
	s_nop 1
	v_cndmask_b32_e64 v64, 0, 1, s[18:19]
	v_cmp_le_f32_e64 s[18:19], s15, v61
	s_nop 1
	v_cndmask_b32_e64 v65, 0, 1, s[18:19]
	v_cmp_le_f32_e64 s[18:19], s15, v60
	s_nop 1
	v_cndmask_b32_e64 v66, 0, 1, s[18:19]
	v_cmp_le_f32_e64 s[18:19], s20, v60
	s_nop 1
	v_addc_co_u32_e64 v60, s[18:19], v62, v66, s[18:19]
	v_cmp_le_f32_e64 s[18:19], s20, v61
	s_nop 1
	v_addc_co_u32_e64 v55, s[18:19], v55, v65, s[18:19]
	v_cmp_le_f32_e64 s[18:19], s20, v56
	s_nop 1
	v_addc_co_u32_e64 v54, s[18:19], v54, v64, s[18:19]
	v_cmp_le_f32_e64 s[18:19], s20, v57
	s_nop 1
	v_addc_co_u32_e64 v53, s[18:19], v53, v63, s[18:19]
	v_cmp_ngt_f32_e64 s[18:19], 0, v18
	s_nop 1
	v_cndmask_b32_e64 v18, 8, 0, s[18:19]
	v_cmp_ngt_f32_e64 s[18:19], 0, v22
	v_or_b32_e32 v18, v60, v18
	v_lshlrev_b32_e32 v18, 8, v18
	v_cndmask_b32_e64 v22, 8, 0, s[18:19]
	v_cmp_ngt_f32_e64 s[18:19], 0, v26
	v_or_b32_e32 v22, v55, v22
	v_lshlrev_b32_e32 v22, 8, v22
	v_cndmask_b32_e64 v26, 8, 0, s[18:19]
	v_cmp_ngt_f32_e64 s[18:19], 0, v30
	v_or_b32_e32 v26, v54, v26
	v_lshlrev_b32_e32 v26, 8, v26
	v_cndmask_b32_e64 v30, 8, 0, s[18:19]
	v_cmp_le_f32_e64 s[18:19], s95, v49
	v_or_b32_e32 v30, v53, v30
	v_lshlrev_b32_e32 v30, 8, v30
	v_cndmask_b32_e64 v53, 0, 1, s[18:19]
	v_cmp_le_f32_e64 s[18:19], s96, v49
	s_nop 1
	v_cndmask_b32_e64 v54, 0, 1, s[18:19]
	v_cmp_le_f32_e64 s[18:19], s97, v49
	s_nop 1
	v_addc_co_u32_e64 v53, s[18:19], v53, v54, s[18:19]
	v_cmp_le_f32_e64 s[18:19], s14, v50
	s_nop 1
	v_cndmask_b32_e64 v54, 0, 1, s[18:19]
	v_cmp_le_f32_e64 s[18:19], s14, v51
	s_nop 1
	v_cndmask_b32_e64 v55, 0, 1, s[18:19]
	v_cmp_le_f32_e64 s[18:19], s14, v48
	s_nop 1
	v_cndmask_b32_e64 v56, 0, 1, s[18:19]
	v_cmp_le_f32_e64 s[18:19], s14, v49
	s_nop 1
	v_cndmask_b32_e64 v57, 0, 1, s[18:19]
	v_cmp_le_f32_e64 s[18:19], s3, v49
	s_nop 1
	v_addc_co_u32_e64 v53, s[18:19], v53, v57, s[18:19]
	v_cmp_le_f32_e64 s[18:19], s3, v48
	s_nop 1
	v_addc_co_u32_e64 v56, s[18:19], v67, v56, s[18:19]
	v_cmp_le_f32_e64 s[18:19], s3, v51
	s_nop 1
	v_addc_co_u32_e64 v55, s[18:19], v114, v55, s[18:19]
	v_cmp_le_f32_e64 s[18:19], s3, v50
	s_nop 1
	v_addc_co_u32_e64 v54, s[18:19], v251, v54, s[18:19]
	v_cmp_le_f32_e64 s[18:19], s15, v49
	s_nop 1
	v_cndmask_b32_e64 v57, 0, 1, s[18:19]
	v_cmp_le_f32_e64 s[18:19], s15, v48
	s_nop 1
	v_cndmask_b32_e64 v60, 0, 1, s[18:19]
	v_cmp_le_f32_e64 s[18:19], s15, v51
	s_nop 1
	v_cndmask_b32_e64 v61, 0, 1, s[18:19]
	v_cmp_le_f32_e64 s[18:19], s15, v50
	s_nop 1
	v_cndmask_b32_e64 v62, 0, 1, s[18:19]
	v_cmp_le_f32_e64 s[18:19], s20, v50
	s_nop 1
	v_addc_co_u32_e64 v50, s[18:19], v54, v62, s[18:19]
	v_cmp_le_f32_e64 s[18:19], s20, v51
	s_nop 1
	v_addc_co_u32_e64 v51, s[18:19], v55, v61, s[18:19]
	v_cmp_le_f32_e64 s[18:19], s20, v48
	s_nop 1
	v_addc_co_u32_e64 v48, s[18:19], v56, v60, s[18:19]
	v_cmp_le_f32_e64 s[18:19], s20, v49
	s_nop 1
	v_addc_co_u32_e64 v49, s[18:19], v53, v57, s[18:19]
	v_cmp_ngt_f32_e64 s[18:19], 0, v19
	s_nop 1
	v_cndmask_b32_e64 v19, 8, 0, s[18:19]
	v_cmp_ngt_f32_e64 s[18:19], 0, v23
	v_or_b32_e32 v19, v50, v19
	v_lshlrev_b32_e32 v19, 12, v19
	v_cndmask_b32_e64 v23, 8, 0, s[18:19]
	v_cmp_ngt_f32_e64 s[18:19], 0, v27
	v_or_b32_e32 v23, v51, v23
	v_lshlrev_b32_e32 v23, 12, v23
	v_cndmask_b32_e64 v27, 8, 0, s[18:19]
	v_cmp_ngt_f32_e64 s[18:19], 0, v31
	v_or3_b32 v18, v59, v18, v19
	v_or3_b32 v22, v58, v22, v23
	v_cndmask_b32_e64 v31, 8, 0, s[18:19]
	v_cmp_le_f32_e64 s[18:19], s95, v47
	v_or_b32_e32 v27, v48, v27
	v_lshlrev_b32_e32 v27, 12, v27
	v_cndmask_b32_e64 v19, 0, 1, s[18:19]
	v_cmp_le_f32_e64 s[18:19], s96, v47
	v_or_b32_e32 v31, v49, v31
	v_or3_b32 v26, v52, v26, v27
	v_cndmask_b32_e64 v23, 0, 1, s[18:19]
	v_cmp_le_f32_e64 s[18:19], s97, v47
	v_lshlrev_b32_e32 v31, 12, v31
	v_or3_b32 v30, v246, v30, v31
	v_addc_co_u32_e64 v19, s[18:19], v19, v23, s[18:19]
	v_cmp_le_f32_e64 s[18:19], s97, v46
	s_nop 1
	v_addc_co_u32_e64 v23, s[18:19], v254, v118, s[18:19]
	v_cmp_le_f32_e64 s[18:19], s97, v45
	s_nop 1
	v_addc_co_u32_e64 v27, s[18:19], v115, v116, s[18:19]
	v_cmp_le_f32_e64 s[18:19], s97, v44
	s_nop 1
	v_addc_co_u32_e64 v31, s[18:19], v109, v252, s[18:19]
	v_cmp_le_f32_e64 s[18:19], s14, v47
	s_nop 1
	v_cndmask_b32_e64 v246, 0, 1, s[18:19]
	v_cmp_le_f32_e64 s[18:19], s14, v46
	s_nop 1
	v_cndmask_b32_e64 v48, 0, 1, s[18:19]
	v_cmp_le_f32_e64 s[18:19], s14, v45
	s_nop 1
	v_cndmask_b32_e64 v49, 0, 1, s[18:19]
	v_cmp_le_f32_e64 s[18:19], s14, v44
	s_nop 1
	v_cndmask_b32_e64 v50, 0, 1, s[18:19]
	v_cmp_le_f32_e64 s[18:19], s3, v44
	s_nop 1
	v_addc_co_u32_e64 v31, s[18:19], v31, v50, s[18:19]
	v_cmp_le_f32_e64 s[18:19], s3, v45
	s_nop 1
	v_addc_co_u32_e64 v27, s[18:19], v27, v49, s[18:19]
	v_cmp_le_f32_e64 s[18:19], s3, v46
	s_nop 1
	v_addc_co_u32_e64 v23, s[18:19], v23, v48, s[18:19]
	v_cmp_le_f32_e64 s[18:19], s3, v47
	s_nop 1
	v_addc_co_u32_e64 v19, s[18:19], v19, v246, s[18:19]
	v_cmp_le_f32_e64 s[18:19], s15, v44
	s_nop 1
	v_cndmask_b32_e64 v246, 0, 1, s[18:19]
	v_cmp_le_f32_e64 s[18:19], s15, v45
	s_nop 1
	v_cndmask_b32_e64 v48, 0, 1, s[18:19]
	v_cmp_le_f32_e64 s[18:19], s15, v46
	s_nop 1
	v_cndmask_b32_e64 v49, 0, 1, s[18:19]
	v_cmp_le_f32_e64 s[18:19], s15, v47
	s_nop 1
	v_cndmask_b32_e64 v50, 0, 1, s[18:19]
	v_cmp_le_f32_e64 s[18:19], s20, v47
	s_nop 1
	v_addc_co_u32_e64 v19, s[18:19], v19, v50, s[18:19]
	v_cmp_le_f32_e64 s[18:19], s20, v46
	s_nop 1
	v_addc_co_u32_e64 v23, s[18:19], v23, v49, s[18:19]
	v_cmp_le_f32_e64 s[18:19], s20, v45
	s_nop 1
	v_addc_co_u32_e64 v27, s[18:19], v27, v48, s[18:19]
	v_cmp_le_f32_e64 s[18:19], s20, v44
	s_nop 1
	v_addc_co_u32_e64 v31, s[18:19], v31, v246, s[18:19]
	v_cmp_ngt_f32_e64 s[18:19], 0, v12
	s_nop 1
	v_cndmask_b32_e64 v12, 8, 0, s[18:19]
	v_cmp_ngt_f32_e64 s[18:19], 0, v8
	v_or_b32_sdwa v12, v19, v12 dst_sel:WORD_1 dst_unused:UNUSED_PAD src0_sel:DWORD src1_sel:DWORD
	s_nop 0
	v_cndmask_b32_e64 v8, 8, 0, s[18:19]
	v_cmp_ngt_f32_e64 s[18:19], 0, v4
	v_or_b32_sdwa v8, v23, v8 dst_sel:WORD_1 dst_unused:UNUSED_PAD src0_sel:DWORD src1_sel:DWORD
	s_nop 0
	v_cndmask_b32_e64 v4, 8, 0, s[18:19]
	v_cmp_ngt_f32_e64 s[18:19], 0, v0
	v_or_b32_sdwa v4, v27, v4 dst_sel:WORD_1 dst_unused:UNUSED_PAD src0_sel:DWORD src1_sel:DWORD
	s_nop 0
	v_cndmask_b32_e64 v0, 8, 0, s[18:19]
	v_cmp_le_f32_e64 s[18:19], s95, v28
	v_or_b32_sdwa v0, v31, v0 dst_sel:WORD_1 dst_unused:UNUSED_PAD src0_sel:DWORD src1_sel:DWORD
	s_nop 0
	v_cndmask_b32_e64 v19, 0, 1, s[18:19]
	v_cmp_le_f32_e64 s[18:19], s95, v29
	s_nop 1
	v_cndmask_b32_e64 v23, 0, 1, s[18:19]
	v_cmp_le_f32_e64 s[18:19], s95, v42
	s_nop 1
	v_cndmask_b32_e64 v27, 0, 1, s[18:19]
	v_cmp_le_f32_e64 s[18:19], s95, v43
	s_nop 1
	v_cndmask_b32_e64 v31, 0, 1, s[18:19]
	v_cmp_le_f32_e64 s[18:19], s96, v28
	s_nop 1
	v_cndmask_b32_e64 v246, 0, 1, s[18:19]
	v_cmp_le_f32_e64 s[18:19], s96, v29
	s_nop 1
	v_cndmask_b32_e64 v44, 0, 1, s[18:19]
	v_cmp_le_f32_e64 s[18:19], s96, v42
	s_nop 1
	v_cndmask_b32_e64 v45, 0, 1, s[18:19]
	v_cmp_le_f32_e64 s[18:19], s96, v43
	s_nop 1
	v_cndmask_b32_e64 v46, 0, 1, s[18:19]
	v_cmp_le_f32_e64 s[18:19], s97, v43
	s_nop 1
	v_addc_co_u32_e64 v31, s[18:19], v31, v46, s[18:19]
	v_cmp_le_f32_e64 s[18:19], s97, v42
	s_nop 1
	v_addc_co_u32_e64 v27, s[18:19], v27, v45, s[18:19]
	v_cmp_le_f32_e64 s[18:19], s97, v29
	s_nop 1
	v_addc_co_u32_e64 v23, s[18:19], v23, v44, s[18:19]
	v_cmp_le_f32_e64 s[18:19], s97, v28
	s_nop 1
	v_addc_co_u32_e64 v19, s[18:19], v19, v246, s[18:19]
	v_cmp_le_f32_e64 s[18:19], s14, v43
	s_nop 1
	v_cndmask_b32_e64 v246, 0, 1, s[18:19]
	v_cmp_le_f32_e64 s[18:19], s14, v42
	s_nop 1
	v_cndmask_b32_e64 v44, 0, 1, s[18:19]
	v_cmp_le_f32_e64 s[18:19], s14, v29
	s_nop 1
	v_cndmask_b32_e64 v45, 0, 1, s[18:19]
	v_cmp_le_f32_e64 s[18:19], s14, v28
	s_nop 1
	v_cndmask_b32_e64 v46, 0, 1, s[18:19]
	v_cmp_le_f32_e64 s[18:19], s3, v28
	s_nop 1
	v_addc_co_u32_e64 v19, s[18:19], v19, v46, s[18:19]
	v_cmp_le_f32_e64 s[18:19], s3, v29
	s_nop 1
	v_addc_co_u32_e64 v23, s[18:19], v23, v45, s[18:19]
	v_cmp_le_f32_e64 s[18:19], s3, v42
	s_nop 1
	v_addc_co_u32_e64 v27, s[18:19], v27, v44, s[18:19]
	v_cmp_le_f32_e64 s[18:19], s3, v43
	s_nop 1
	v_addc_co_u32_e64 v31, s[18:19], v31, v246, s[18:19]
	v_cmp_le_f32_e64 s[18:19], s15, v28
	s_nop 1
	v_cndmask_b32_e64 v246, 0, 1, s[18:19]
	v_cmp_le_f32_e64 s[18:19], s15, v29
	s_nop 1
	v_cndmask_b32_e64 v44, 0, 1, s[18:19]
	v_cmp_le_f32_e64 s[18:19], s15, v42
	s_nop 1
	v_cndmask_b32_e64 v45, 0, 1, s[18:19]
	v_cmp_le_f32_e64 s[18:19], s15, v43
	s_nop 1
	v_cndmask_b32_e64 v46, 0, 1, s[18:19]
	v_cmp_le_f32_e64 s[18:19], s20, v43
	s_nop 1
	v_addc_co_u32_e64 v31, s[18:19], v31, v46, s[18:19]
	v_cmp_le_f32_e64 s[18:19], s20, v42
	s_nop 1
	v_addc_co_u32_e64 v27, s[18:19], v27, v45, s[18:19]
	v_cmp_le_f32_e64 s[18:19], s20, v29
	s_nop 1
	v_addc_co_u32_e64 v23, s[18:19], v23, v44, s[18:19]
	v_cmp_le_f32_e64 s[18:19], s20, v28
	s_nop 1
	v_addc_co_u32_e64 v19, s[18:19], v19, v246, s[18:19]
	v_cmp_ngt_f32_e64 s[18:19], 0, v13
	s_nop 1
	v_cndmask_b32_e64 v13, 8, 0, s[18:19]
	v_cmp_ngt_f32_e64 s[18:19], 0, v9
	v_or_b32_e32 v13, v31, v13
	v_lshlrev_b32_e32 v13, 20, v13
	v_cndmask_b32_e64 v9, 8, 0, s[18:19]
	v_cmp_ngt_f32_e64 s[18:19], 0, v5
	v_or_b32_e32 v9, v27, v9
	v_lshlrev_b32_e32 v9, 20, v9
	v_cndmask_b32_e64 v5, 8, 0, s[18:19]
	v_cmp_ngt_f32_e64 s[18:19], 0, v1
	v_or_b32_e32 v5, v23, v5
	v_lshlrev_b32_e32 v5, 20, v5
	v_cndmask_b32_e64 v1, 8, 0, s[18:19]
	v_or_b32_e32 v1, v19, v1
	v_lshlrev_b32_e32 v1, 20, v1
	v_cmp_le_f32_e64 s[18:19], s95, v21
	v_or3_b32 v18, v18, v0, v1
	v_or3_b32 v19, v22, v4, v5
	v_cndmask_b32_e64 v0, 0, 1, s[18:19]
	v_cmp_le_f32_e64 s[18:19], s95, v20
	v_or3_b32 v8, v26, v8, v9
	v_or3_b32 v9, v30, v12, v13
	v_cndmask_b32_e64 v1, 0, 1, s[18:19]
	v_cmp_le_f32_e64 s[18:19], s95, v25
	s_nop 1
	v_cndmask_b32_e64 v4, 0, 1, s[18:19]
	v_cmp_le_f32_e64 s[18:19], s95, v24
	s_nop 1
	v_cndmask_b32_e64 v5, 0, 1, s[18:19]
	v_cmp_le_f32_e64 s[18:19], s96, v21
	s_nop 1
	v_cndmask_b32_e64 v12, 0, 1, s[18:19]
	v_cmp_le_f32_e64 s[18:19], s96, v20
	s_nop 1
	v_cndmask_b32_e64 v13, 0, 1, s[18:19]
	v_cmp_le_f32_e64 s[18:19], s96, v25
	s_nop 1
	v_cndmask_b32_e64 v22, 0, 1, s[18:19]
	v_cmp_le_f32_e64 s[18:19], s96, v24
	s_nop 1
	v_cndmask_b32_e64 v23, 0, 1, s[18:19]
	v_cmp_le_f32_e64 s[18:19], s97, v24
	s_nop 1
	v_addc_co_u32_e64 v5, s[18:19], v5, v23, s[18:19]
	v_cmp_le_f32_e64 s[18:19], s97, v25
	s_nop 1
	v_addc_co_u32_e64 v4, s[18:19], v4, v22, s[18:19]
	v_cmp_le_f32_e64 s[18:19], s97, v20
	s_nop 1
	v_addc_co_u32_e64 v1, s[18:19], v1, v13, s[18:19]
	v_cmp_le_f32_e64 s[18:19], s97, v21
	s_nop 1
	v_addc_co_u32_e64 v0, s[18:19], v0, v12, s[18:19]
	v_cmp_le_f32_e64 s[18:19], s14, v24
	s_nop 1
	v_cndmask_b32_e64 v12, 0, 1, s[18:19]
	v_cmp_le_f32_e64 s[18:19], s14, v25
	s_nop 1
	v_cndmask_b32_e64 v13, 0, 1, s[18:19]
	v_cmp_le_f32_e64 s[18:19], s14, v20
	s_nop 1
	v_cndmask_b32_e64 v22, 0, 1, s[18:19]
	v_cmp_le_f32_e64 s[18:19], s14, v21
	s_nop 1
	v_cndmask_b32_e64 v23, 0, 1, s[18:19]
	v_cmp_le_f32_e64 s[18:19], s3, v21
	s_nop 1
	v_addc_co_u32_e64 v0, s[18:19], v0, v23, s[18:19]
	v_cmp_le_f32_e64 s[18:19], s3, v20
	s_nop 1
	v_addc_co_u32_e64 v1, s[18:19], v1, v22, s[18:19]
	v_cmp_le_f32_e64 s[18:19], s3, v25
	s_nop 1
	v_addc_co_u32_e64 v4, s[18:19], v4, v13, s[18:19]
	v_cmp_le_f32_e64 s[18:19], s3, v24
	s_nop 1
	v_addc_co_u32_e64 v5, s[18:19], v5, v12, s[18:19]
	v_cmp_le_f32_e64 s[18:19], s15, v21
	s_nop 1
	v_cndmask_b32_e64 v12, 0, 1, s[18:19]
	v_cmp_le_f32_e64 s[18:19], s15, v20
	s_nop 1
	v_cndmask_b32_e64 v13, 0, 1, s[18:19]
	v_cmp_le_f32_e64 s[18:19], s15, v25
	s_nop 1
	v_cndmask_b32_e64 v22, 0, 1, s[18:19]
	v_cmp_le_f32_e64 s[18:19], s15, v24
	s_nop 1
	v_cndmask_b32_e64 v23, 0, 1, s[18:19]
	v_cmp_le_f32_e64 s[18:19], s20, v24
	s_nop 1
	v_addc_co_u32_e64 v5, s[18:19], v5, v23, s[18:19]
	v_cmp_le_f32_e64 s[18:19], s20, v25
	s_nop 1
	v_addc_co_u32_e64 v4, s[18:19], v4, v22, s[18:19]
	v_cmp_le_f32_e64 s[18:19], s20, v20
	s_nop 1
	v_addc_co_u32_e64 v1, s[18:19], v1, v13, s[18:19]
	v_cmp_le_f32_e64 s[18:19], s20, v21
	s_nop 1
	v_addc_co_u32_e64 v0, s[18:19], v0, v12, s[18:19]
	v_cmp_ngt_f32_e64 s[18:19], 0, v2
	s_nop 1
	v_cndmask_b32_e64 v2, 8, 0, s[18:19]
	v_cmp_ngt_f32_e64 s[18:19], 0, v6
	v_or_b32_sdwa v13, v5, v2 dst_sel:BYTE_3 dst_unused:UNUSED_PAD src0_sel:DWORD src1_sel:DWORD
	s_nop 0
	v_cndmask_b32_e64 v6, 8, 0, s[18:19]
	v_cmp_ngt_f32_e64 s[18:19], 0, v10
	v_or_b32_sdwa v6, v4, v6 dst_sel:BYTE_3 dst_unused:UNUSED_PAD src0_sel:DWORD src1_sel:DWORD
	v_pk_mul_f32 v[4:5], v[38:39], v[16:17] op_sel_hi:[1,0]
	v_cndmask_b32_e64 v10, 8, 0, s[18:19]
	v_cmp_ngt_f32_e64 s[18:19], 0, v14
	v_or_b32_sdwa v10, v1, v10 dst_sel:BYTE_3 dst_unused:UNUSED_PAD src0_sel:DWORD src1_sel:DWORD
	s_nop 0
	v_cndmask_b32_e64 v12, 8, 0, s[18:19]
	v_or_b32_sdwa v12, v0, v12 dst_sel:BYTE_3 dst_unused:UNUSED_PAD src0_sel:DWORD src1_sel:DWORD
	v_pk_mul_f32 v[0:1], v[40:41], v[16:17] op_sel_hi:[1,0]
	s_nop 0
	v_cmp_le_f32_e64 s[18:19], s95, v1
	s_nop 1
	v_cndmask_b32_e64 v2, 0, 1, s[18:19]
	v_cmp_le_f32_e64 s[18:19], s95, v0
	s_nop 1
	v_cndmask_b32_e64 v14, 0, 1, s[18:19]
	v_cmp_le_f32_e64 s[18:19], s95, v5
	s_nop 1
	v_cndmask_b32_e64 v16, 0, 1, s[18:19]
	v_cmp_le_f32_e64 s[18:19], s95, v4
	s_nop 1
	v_cndmask_b32_e64 v20, 0, 1, s[18:19]
	v_cmp_le_f32_e64 s[18:19], s96, v1
	s_nop 1
	v_cndmask_b32_e64 v21, 0, 1, s[18:19]
	v_cmp_le_f32_e64 s[18:19], s96, v0
	s_nop 1
	v_cndmask_b32_e64 v22, 0, 1, s[18:19]
	v_cmp_le_f32_e64 s[18:19], s96, v5
	s_nop 1
	v_cndmask_b32_e64 v23, 0, 1, s[18:19]
	v_cmp_le_f32_e64 s[18:19], s96, v4
	s_nop 1
	v_cndmask_b32_e64 v24, 0, 1, s[18:19]
	v_cmp_le_f32_e64 s[18:19], s97, v4
	s_nop 1
	v_addc_co_u32_e64 v20, s[18:19], v20, v24, s[18:19]
	v_cmp_le_f32_e64 s[18:19], s97, v5
	s_nop 1
	v_addc_co_u32_e64 v16, s[18:19], v16, v23, s[18:19]
	v_cmp_le_f32_e64 s[18:19], s97, v0
	s_nop 1
	v_addc_co_u32_e64 v14, s[18:19], v14, v22, s[18:19]
	v_cmp_le_f32_e64 s[18:19], s97, v1
	s_nop 1
	v_addc_co_u32_e64 v2, s[18:19], v2, v21, s[18:19]
	v_cmp_le_f32_e64 s[18:19], s14, v4
	s_nop 1
	v_cndmask_b32_e64 v21, 0, 1, s[18:19]
	v_cmp_le_f32_e64 s[18:19], s14, v5
	s_nop 1
	v_cndmask_b32_e64 v22, 0, 1, s[18:19]
	v_cmp_le_f32_e64 s[18:19], s14, v0
	s_nop 1
	v_cndmask_b32_e64 v23, 0, 1, s[18:19]
	v_cmp_le_f32_e64 s[18:19], s14, v1
	s_nop 1
	v_cndmask_b32_e64 v24, 0, 1, s[18:19]
	v_cmp_le_f32_e64 s[18:19], s3, v1
	s_nop 1
	v_addc_co_u32_e64 v2, s[18:19], v2, v24, s[18:19]
	v_cmp_le_f32_e64 s[18:19], s3, v0
	s_nop 1
	v_addc_co_u32_e64 v14, s[18:19], v14, v23, s[18:19]
	v_cmp_le_f32_e64 s[18:19], s3, v5
	s_nop 1
	v_addc_co_u32_e64 v16, s[18:19], v16, v22, s[18:19]
	v_cmp_le_f32_e64 s[18:19], s3, v4
	s_nop 1
	v_addc_co_u32_e64 v20, s[18:19], v20, v21, s[18:19]
	v_cmp_le_f32_e64 s[18:19], s15, v1
	s_nop 1
	v_cndmask_b32_e64 v21, 0, 1, s[18:19]
	v_cmp_le_f32_e64 s[18:19], s15, v0
	s_nop 1
	v_cndmask_b32_e64 v22, 0, 1, s[18:19]
	v_cmp_le_f32_e64 s[18:19], s15, v5
	s_nop 1
	v_cndmask_b32_e64 v23, 0, 1, s[18:19]
	v_cmp_le_f32_e64 s[18:19], s15, v4
	s_nop 1
	v_cndmask_b32_e64 v24, 0, 1, s[18:19]
	v_cmp_le_f32_e64 s[18:19], s20, v4
	s_nop 1
	v_addc_co_u32_e64 v4, s[18:19], v20, v24, s[18:19]
	v_cmp_le_f32_e64 s[18:19], s20, v5
	s_nop 1
	v_addc_co_u32_e64 v5, s[18:19], v16, v23, s[18:19]
	v_cmp_le_f32_e64 s[18:19], s20, v0
	s_nop 1
	v_addc_co_u32_e64 v0, s[18:19], v14, v22, s[18:19]
	v_cmp_le_f32_e64 s[18:19], s20, v1
	s_nop 1
	v_addc_co_u32_e64 v1, s[18:19], v2, v21, s[18:19]
	v_cmp_ngt_f32_e64 s[18:19], 0, v3
	s_nop 1
	v_cndmask_b32_e64 v2, 8, 0, s[18:19]
	v_cmp_ngt_f32_e64 s[18:19], 0, v7
	v_or_b32_e32 v2, v4, v2
	v_lshlrev_b32_e32 v4, 28, v2
	v_cndmask_b32_e64 v3, 8, 0, s[18:19]
	v_cmp_ngt_f32_e64 s[18:19], 0, v11
	v_or_b32_e32 v3, v5, v3
	v_lshlrev_b32_e32 v5, 28, v3
	v_cndmask_b32_e64 v7, 8, 0, s[18:19]
	v_cmp_ngt_f32_e64 s[18:19], 0, v15
	v_or_b32_e32 v0, v0, v7
	v_lshlrev_b32_e32 v0, 28, v0
	v_cndmask_b32_e64 v11, 8, 0, s[18:19]
	v_or_b32_e32 v1, v1, v11
	v_lshlrev_b32_e32 v1, 28, v1
	v_or3_b32 v3, v9, v12, v1
	v_or3_b32 v2, v8, v10, v0
	v_or3_b32 v1, v19, v6, v5
	v_or3_b32 v0, v18, v13, v4
	global_store_dwordx4 v[36:37], v[0:3], off
	s_and_saveexec_b64 s[18:19], s[0:1]
	s_cbranch_execz .Lmy_tq_19
	v_readlane_b32 s36, v238, 16
	v_readlane_b32 s45, v238, 25
	v_readlane_b32 s47, v238, 27
	v_readlane_b32 s44, v238, 24
	v_readlane_b32 s46, v238, 26
	v_mov_b32_e32 v0, s45
	v_mov_b32_e32 v1, s47
	v_cndmask_b32_e64 v1, v0, v1, s[16:17]
	v_mov_b32_e32 v0, s44
	v_mov_b32_e32 v2, s46
	v_cndmask_b32_e64 v0, v0, v2, s[16:17]
	v_lshlrev_b32_e32 v246, 2, v85
	v_mul_f32_e32 v2, 0x3e2aaaab, v17
	v_lshl_add_u64 v[0:1], v[0:1], 0, v[246:247]
	v_cndmask_b32_e32 v2, 1.0, v2, vcc
	v_readlane_b32 s37, v238, 17
	v_readlane_b32 s38, v238, 18
	v_readlane_b32 s39, v238, 19
	v_readlane_b32 s40, v238, 20
	v_readlane_b32 s41, v238, 21
	v_readlane_b32 s42, v238, 22
	v_readlane_b32 s43, v238, 23
	v_readlane_b32 s48, v238, 28
	v_readlane_b32 s49, v238, 29
	v_readlane_b32 s50, v238, 30
	v_readlane_b32 s51, v238, 31
	global_store_dword v[0:1], v2, off
	s_branch .Lmy_tq_19

.Lmy_tq_skip:
	s_waitcnt vmcnt(0)
	s_barrier
	s_mov_b64 s[10:11], exec
	v_readlane_b32 s0, v237, 0
	v_readlane_b32 s1, v237, 1
	s_and_b64 s[0:1], s[10:11], s[0:1]
	s_mov_b64 exec, s[0:1]
	s_cbranch_execz .LBB0_635
	s_mov_b64 s[0:1], src_shared_base
	v_mov_b32_e32 v0, 0x12800
	v_mov_b32_e32 v1, s1
	s_waitcnt vmcnt(0) expcnt(0) lgkmcnt(0)
	flat_load_dword v2, v[0:1] sc0 sc1
	s_waitcnt vmcnt(0)
	v_mov_b32_e32 v0, 0x12804
	flat_load_dword v0, v[0:1] sc0 sc1
	s_waitcnt vmcnt(0) lgkmcnt(0)
	v_cmp_eq_u32_e32 vcc, 0, v2
	s_and_saveexec_b64 s[12:13], vcc
	s_cbranch_execz .LBB0_599
	s_add_u32 s20, s92, 0x1000
	s_addc_u32 s21, s93, 0
	s_add_u32 s22, s92, 0x1100
	s_addc_u32 s23, s93, 0
	s_add_u32 s48, s92, 0x1200
	s_addc_u32 s49, s93, 0
	s_add_u32 s54, s92, 0x1300
	s_addc_u32 s55, s93, 0
	s_mov_b32 s0, 1
	v_mov_b32_e32 v16, 0
	s_branch .LBB0_587
